# select phase: deferred wait for next unit weights + dynamic LDS-ticket distribution of indexer key tiles over the 8 waves
# speedup vs baseline: 1.2162x; 1.2162x over previous
.LBB0_684:
	s_lshl_b32 s4, s6, 2
	s_add_i32 s52, s4, 0x100
	v_mov_b32_e32 v3, v202
	v_mov_b32_e32 v133, 0
	s_mov_b32 s12, 0
	v_mov_b32_e32 v2, 0
	s_andn2_b64 vcc, exec, s[54:55]
	v_mov_b32_e32 v44, 0
	v_mov_b32_e32 v45, 0
	v_mov_b32_e32 v46, 0
	v_mov_b32_e32 v47, 0
	v_mov_b32_e32 v48, 0
	v_mov_b32_e32 v49, 0
	v_mov_b32_e32 v50, 0
	v_mov_b32_e32 v51, 0
	v_mov_b32_e32 v52, 0
	v_mov_b32_e32 v53, 0
	v_mov_b32_e32 v54, 0
	v_mov_b32_e32 v55, 0
	v_mov_b32_e32 v56, 0
	v_mov_b32_e32 v57, 0
	v_mov_b32_e32 v58, 0
	v_mov_b32_e32 v59, 0
	v_mov_b32_e32 v135, 0
	v_mov_b32_e32 v37, 0
	v_mov_b32_e32 v137, 0
	v_mov_b32_e32 v39, 0
	v_mov_b32_e32 v139, 0
	v_mov_b32_e32 v41, 0
	v_mov_b32_e32 v141, 0
	v_mov_b32_e32 v43, 0
	v_mov_b32_e32 v134, 0
	v_mov_b32_e32 v36, 0
	v_mov_b32_e32 v136, 0
	v_mov_b32_e32 v38, 0
	v_mov_b32_e32 v138, 0
	v_mov_b32_e32 v40, 0
	v_mov_b32_e32 v140, 0
	v_mov_b32_e32 v42, 0
	s_cbranch_vccnz .LBB0_686
	s_ashr_i32 s51, s50, 31
	v_lshrrev_b32_e32 v4, 3, v3
	v_and_b32_e32 v6, 4, v3
	s_lshl_b64 s[4:5], s[50:51], 13
	s_ashr_i32 s6, s52, 31
	v_and_or_b32 v4, v4, 2, v6
	s_add_u32 s7, s4, s52
	v_bfe_u32 v14, v3, 5, 1
	v_and_b32_e32 v5, 3, v3
	v_lshrrev_b32_e32 v4, 1, v4
	v_lshrrev_b32_e32 v3, 1, v3
	v_and_or_b32 v3, v3, 4, v5
	v_or_b32_e32 v6, s7, v4
	s_movk_i32 s4, 0x1200
	v_mov_b64_e32 v[4:5], s[38:39]
	s_addc_u32 s6, s5, s6
	v_mad_u64_u32 v[8:9], s[4:5], v6, s4, v[4:5]
	v_mov_b32_e32 v4, 0x1200
	v_mad_i32_i24 v9, s6, v4, v9
	v_lshl_or_b32 v4, v14, 1, s7
	v_mov_b32_e32 v5, s6
	v_lshlrev_b64 v[4:5], 5, v[4:5]
	v_lshl_add_u64 v[6:7], s[42:43], 0, v[4:5]
	v_or_b32_e32 v4, 32, v4
	v_lshl_add_u64 v[12:13], s[42:43], 0, v[4:5]
	global_load_dwordx4 v[36:39], v[6:7], off
	global_load_dwordx4 v[40:43], v[6:7], off offset:16
	v_lshlrev_b32_e32 v10, 7, v3
	global_load_dwordx4 v[134:137], v[12:13], off
	v_mov_b32_e32 v11, 0
	v_lshl_add_u64 v[8:9], v[8:9], 0, v[10:11]
	v_lshlrev_b32_e32 v10, 4, v14
	v_lshl_add_u64 v[14:15], v[8:9], 0, v[10:11]
	global_load_dwordx4 v[138:141], v[12:13], off offset:16
	global_load_dwordx4 v[44:47], v[14:15], off offset:3072
	global_load_dwordx4 v[48:51], v[14:15], off offset:3104
	global_load_dwordx4 v[52:55], v[14:15], off offset:3136
	global_load_dwordx4 v[56:59], v[14:15], off offset:3168

.LBB0_694:
	s_or_b64 exec, exec, s[6:7]
	v_cmp_gt_i32_e64 s[8:9], 4, v144
	s_and_saveexec_b64 s[6:7], s[8:9]
	s_cbranch_execz .LBB0_696
	v_lshl_add_u32 v1, v144, 5, 0
	v_add_u32_e32 v1, 0x25800, v1
	ds_write_b128 v1, v[64:67]
	ds_write2_b32 v1, v2, v2 offset0:5 offset1:6
	v_mov_b32_e32 v3, 24
	ds_write_b32 v1, v3 offset:512
.LBB0_696:
	s_or_b64 exec, exec, s[6:7]
	s_add_i32 s6, s52, 3
	s_ashr_i32 s13, s6, 5
	s_ashr_i32 s51, s50, 31
	s_and_b32 s14, s13, 0xffffffe0
	s_add_i32 s10, s14, 32
	s_ashr_i32 s53, s60, 6
	s_lshl_b64 s[6:7], s[50:51], 20
	v_and_b32_e32 v145, 63, v144
	v_bfe_u32 v162, v144, 5, 1
	s_add_u32 s6, s40, s6
	v_lshlrev_b32_e32 v163, 1, v162
	s_addc_u32 s7, s41, s7
	v_lshlrev_b32_e32 v132, 4, v145
	v_and_b32_e32 v164, 31, v144
	v_lshlrev_b32_e32 v167, 16, v162
	v_lshl_add_u32 v165, v162, 13, s68
	v_add_u32_e32 v1, s52, v163
	v_lshl_add_u64 v[156:157], s[6:7], 0, v[132:133]
	v_lshl_add_u32 v166, v145, 2, s71
	s_waitcnt lgkmcnt(0)
	s_barrier
	s_min_i32 s6, s53, s13
	s_ashr_i32 s7, s6, 31
	s_lshl_b64 s[6:7], s[6:7], 12
	v_lshl_add_u64 v[4:5], v[156:157], 0, s[6:7]
	global_load_dwordx4 v[80:83], v[4:5], off
	global_load_dwordx4 v[76:79], v[4:5], off offset:1024
	global_load_dwordx4 v[72:75], v[4:5], off offset:2048
	global_load_dwordx4 v[68:71], v[4:5], off offset:3072
	s_add_i32 s6, s53, 8
	s_min_i32 s6, s6, s13
	s_ashr_i32 s7, s6, 31
	s_lshl_b64 s[6:7], s[6:7], 12
	v_lshl_add_u64 v[4:5], v[156:157], 0, s[6:7]
	global_load_dwordx4 v[96:99], v[4:5], off
	global_load_dwordx4 v[92:95], v[4:5], off offset:1024
	global_load_dwordx4 v[88:91], v[4:5], off offset:2048
	global_load_dwordx4 v[84:87], v[4:5], off offset:3072
	s_add_i32 s6, s53, 16
	s_min_i32 s6, s6, s13
	s_ashr_i32 s7, s6, 31
	s_lshl_b64 s[6:7], s[6:7], 12
	v_lshl_add_u64 v[4:5], v[156:157], 0, s[6:7]
	global_load_dwordx4 v[112:115], v[4:5], off
	global_load_dwordx4 v[108:111], v[4:5], off offset:1024
	global_load_dwordx4 v[104:107], v[4:5], off offset:2048
	global_load_dwordx4 v[100:103], v[4:5], off offset:3072
	s_waitcnt vmcnt(12)
	v_swap_b32 v135, v36
	v_swap_b32 v137, v38
	v_swap_b32 v139, v40
	v_swap_b32 v141, v42
	v_add_u32_e32 v132, 1, v1
	v_lshlrev_b32_e32 v168, 2, v164
	v_mov_b32_e32 v172, 0x25a00
	s_mov_b32 s16, s53
	s_add_i32 s17, s53, 8
	s_add_i32 s18, s53, 16
	s_mov_b32 s19, -1
	s_mov_b32 s10, 0
	v_add_u32_e32 v175, v167, v168
	s_mov_b64 exec, 1
	ds_add_rtn_u32 v171, v172, v149
	s_mov_b64 exec, -1
	s_waitcnt lgkmcnt(0)
	v_readfirstlane_b32 s15, v171
.Lidx_loop:
	s_mov_b32 s14, s19
	s_mov_b32 s19, s15
	s_mov_b64 exec, 1
	ds_add_rtn_u32 v171, v172, v149
	s_mov_b64 exec, -1
	s_min_i32 s6, s19, s13
	s_ashr_i32 s7, s6, 31
	s_lshl_b64 s[6:7], s[6:7], 12
	s_waitcnt vmcnt(12)
	v_lshl_add_u64 v[116:117], v[156:157], 0, s[6:7]
	global_load_dwordx4 v[128:131], v[116:117], off
	global_load_dwordx4 v[124:127], v[116:117], off offset:1024
	global_load_dwordx4 v[120:123], v[116:117], off offset:2048
	s_nop 0
	global_load_dwordx4 v[116:119], v[116:117], off offset:3072
	s_cmp_gt_i32 s16, s13
	s_cbranch_scc1 .Lidx_exit_prev1
	s_waitcnt vmcnt(15)
	v_mfma_f32_32x32x16_bf16 v[20:35], v[44:47], v[80:83], 0
	s_waitcnt vmcnt(14)
	v_mfma_f32_32x32x16_bf16 v[20:35], v[48:51], v[76:79], v[20:35]
	s_waitcnt vmcnt(13)
	v_mfma_f32_32x32x16_bf16 v[20:35], v[52:55], v[72:75], v[20:35]
	s_waitcnt vmcnt(12)
	v_mfma_f32_32x32x16_bf16 v[20:35], v[56:59], v[68:71], v[20:35]
	s_cmp_lt_i32 s14, 0
	s_cbranch_scc1 .Lidx_nopost0
	v_max_i32_e32 v177, 0, v4
	v_max_i32_e32 v176, 0, v12
	v_max_i32_e32 v179, 0, v5
	v_pk_fma_f32 v[176:177], v[134:135], v[176:177], 0 op_sel_hi:[1,1,0]
	v_max_i32_e32 v178, 0, v13
	v_max_i32_e32 v181, 0, v6
	v_max_i32_e32 v180, 0, v14
	v_pk_fma_f32 v[176:177], v[36:37], v[178:179], v[176:177]
	v_lshl_or_b32 v188, s14, 5, v164
	v_pk_fma_f32 v[176:177], v[136:137], v[180:181], v[176:177]
	v_max_i32_e32 v179, 0, v7
	v_max_i32_e32 v178, 0, v15
	v_pk_fma_f32 v[176:177], v[38:39], v[178:179], v[176:177]
	v_max_i32_e32 v179, 0, v8
	v_max_i32_e32 v178, 0, v16
	v_pk_fma_f32 v[176:177], v[138:139], v[178:179], v[176:177]
	v_max_i32_e32 v179, 0, v9
	v_max_i32_e32 v178, 0, v17
	v_pk_fma_f32 v[176:177], v[40:41], v[178:179], v[176:177]
	v_max_i32_e32 v179, 0, v10
	v_max_i32_e32 v178, 0, v18
	v_pk_fma_f32 v[176:177], v[140:141], v[178:179], v[176:177]
	v_max_i32_e32 v179, 0, v11
	v_max_i32_e32 v178, 0, v19
	v_pk_fma_f32 v[176:177], v[42:43], v[178:179], v[176:177]
	s_nop 0
	v_and_b32_e32 v183, 0x7fffffff, v177
	v_and_b32_e32 v182, 0x7fffffff, v176
	v_xor_b32_e32 v185, -1, v177
	v_pk_add_f32 v[182:183], v[182:183], 0 neg_lo:[1,1] neg_hi:[1,1]
	v_cmp_gt_i32_e32 vcc, 0, v177
	v_xor_b32_e32 v184, -1, v176
	s_nop 0
	v_cndmask_b32_e32 v186, v183, v185, vcc
	v_cmp_gt_i32_e32 vcc, 0, v176
	s_nop 1
	v_cndmask_b32_e32 v187, v182, v184, vcc
	v_cmp_le_i32_e32 vcc, v188, v132
	s_nop 1
	v_cndmask_b32_e32 v187, 0, v187, vcc
	v_cmp_le_i32_e32 vcc, v188, v1
	v_lshl_add_u32 v189, s14, 7, v175
	s_nop 0
	v_cndmask_b32_e32 v186, 0, v186, vcc
	ds_write2st64_b32 v189, v186, v187 offset1:128
	v_lshrrev_b32_e32 v190, 20, v186
	v_cmp_eq_u32_e32 vcc, 0, v186
	v_lshrrev_b32_e32 v191, 17, v186
	v_and_b32_e32 v190, 0xffc, v190
	v_and_b32_e32 v191, 16, v191
	v_add_u32_e32 v190, v165, v190
	v_lshlrev_b32_e64 v191, v191, 1
	v_cndmask_b32_e32 v190, v190, v166, vcc
	v_cndmask_b32_e64 v191, v191, 0, vcc
	ds_add_u32 v190, v191
	v_lshrrev_b32_e32 v190, 20, v187
	v_cmp_eq_u32_e32 vcc, 0, v187
	v_lshrrev_b32_e32 v191, 17, v187
	v_and_b32_e32 v190, 0xffc, v190
	v_and_b32_e32 v191, 16, v191
	v_add3_u32 v190, v165, v190, s73
	v_lshlrev_b32_e64 v191, v191, 1
	v_cndmask_b32_e32 v190, v190, v166, vcc
	v_cndmask_b32_e64 v191, v191, 0, vcc
	ds_add_u32 v190, v191
	s_waitcnt lgkmcnt(3)
	s_branch .Lidx_join0

.Lidx_join0:
	v_readfirstlane_b32 s15, v171
	s_mov_b32 s14, s16
	s_mov_b32 s16, s15
	s_mov_b64 exec, 1
	ds_add_rtn_u32 v171, v172, v149
	s_mov_b64 exec, -1
	s_min_i32 s6, s16, s13
	s_ashr_i32 s7, s6, 31
	s_lshl_b64 s[6:7], s[6:7], 12
	s_waitcnt vmcnt(12)
	v_lshl_add_u64 v[68:69], v[156:157], 0, s[6:7]
	global_load_dwordx4 v[80:83], v[68:69], off
	global_load_dwordx4 v[76:79], v[68:69], off offset:1024
	global_load_dwordx4 v[72:75], v[68:69], off offset:2048
	s_nop 0
	global_load_dwordx4 v[68:71], v[68:69], off offset:3072
	s_cmp_gt_i32 s17, s13
	s_cbranch_scc1 .Lidx_exit_prev0
	s_waitcnt vmcnt(15)
	v_mfma_f32_32x32x16_bf16 v[4:19], v[44:47], v[96:99], 0
	s_waitcnt vmcnt(14)
	v_mfma_f32_32x32x16_bf16 v[4:19], v[48:51], v[92:95], v[4:19]
	s_waitcnt vmcnt(13)
	v_mfma_f32_32x32x16_bf16 v[4:19], v[52:55], v[88:91], v[4:19]
	s_waitcnt vmcnt(12)
	v_mfma_f32_32x32x16_bf16 v[4:19], v[56:59], v[84:87], v[4:19]
	v_max_i32_e32 v177, 0, v20
	v_max_i32_e32 v176, 0, v28
	v_max_i32_e32 v179, 0, v21
	v_pk_fma_f32 v[176:177], v[134:135], v[176:177], 0 op_sel_hi:[1,1,0]
	v_max_i32_e32 v178, 0, v29
	v_max_i32_e32 v181, 0, v22
	v_max_i32_e32 v180, 0, v30
	v_pk_fma_f32 v[176:177], v[36:37], v[178:179], v[176:177]
	v_lshl_or_b32 v188, s14, 5, v164
	v_pk_fma_f32 v[176:177], v[136:137], v[180:181], v[176:177]
	v_max_i32_e32 v179, 0, v23
	v_max_i32_e32 v178, 0, v31
	v_pk_fma_f32 v[176:177], v[38:39], v[178:179], v[176:177]
	v_max_i32_e32 v179, 0, v24
	v_max_i32_e32 v178, 0, v32
	v_pk_fma_f32 v[176:177], v[138:139], v[178:179], v[176:177]
	v_max_i32_e32 v179, 0, v25
	v_max_i32_e32 v178, 0, v33
	v_pk_fma_f32 v[176:177], v[40:41], v[178:179], v[176:177]
	v_max_i32_e32 v179, 0, v26
	v_max_i32_e32 v178, 0, v34
	v_pk_fma_f32 v[176:177], v[140:141], v[178:179], v[176:177]
	v_max_i32_e32 v179, 0, v27
	v_max_i32_e32 v178, 0, v35
	v_pk_fma_f32 v[176:177], v[42:43], v[178:179], v[176:177]
	s_nop 0
	v_and_b32_e32 v183, 0x7fffffff, v177
	v_and_b32_e32 v182, 0x7fffffff, v176
	v_xor_b32_e32 v185, -1, v177
	v_pk_add_f32 v[182:183], v[182:183], 0 neg_lo:[1,1] neg_hi:[1,1]
	v_cmp_gt_i32_e32 vcc, 0, v177
	v_xor_b32_e32 v184, -1, v176
	s_nop 0
	v_cndmask_b32_e32 v186, v183, v185, vcc
	v_cmp_gt_i32_e32 vcc, 0, v176
	s_nop 1
	v_cndmask_b32_e32 v187, v182, v184, vcc
	v_cmp_le_i32_e32 vcc, v188, v132
	s_nop 1
	v_cndmask_b32_e32 v187, 0, v187, vcc
	v_cmp_le_i32_e32 vcc, v188, v1
	v_lshl_add_u32 v189, s14, 7, v175
	s_nop 0
	v_cndmask_b32_e32 v186, 0, v186, vcc
	ds_write2st64_b32 v189, v186, v187 offset1:128
	v_lshrrev_b32_e32 v190, 20, v186
	v_cmp_eq_u32_e32 vcc, 0, v186
	v_lshrrev_b32_e32 v191, 17, v186
	v_and_b32_e32 v190, 0xffc, v190
	v_and_b32_e32 v191, 16, v191
	v_add_u32_e32 v190, v165, v190
	v_lshlrev_b32_e64 v191, v191, 1
	v_cndmask_b32_e32 v190, v190, v166, vcc
	v_cndmask_b32_e64 v191, v191, 0, vcc
	ds_add_u32 v190, v191
	v_lshrrev_b32_e32 v190, 20, v187
	v_cmp_eq_u32_e32 vcc, 0, v187
	v_lshrrev_b32_e32 v191, 17, v187
	v_and_b32_e32 v190, 0xffc, v190
	v_and_b32_e32 v191, 16, v191
	v_add3_u32 v190, v165, v190, s73
	v_lshlrev_b32_e64 v191, v191, 1
	v_cndmask_b32_e32 v190, v190, v166, vcc
	v_cndmask_b32_e64 v191, v191, 0, vcc
	ds_add_u32 v190, v191
	s_waitcnt lgkmcnt(3)
	v_readfirstlane_b32 s15, v171
	s_mov_b32 s14, s17
	s_mov_b32 s17, s15
	s_mov_b64 exec, 1
	ds_add_rtn_u32 v171, v172, v149
	s_mov_b64 exec, -1
	s_min_i32 s6, s17, s13
	s_ashr_i32 s7, s6, 31
	s_lshl_b64 s[6:7], s[6:7], 12
	s_waitcnt vmcnt(12)
	v_lshl_add_u64 v[84:85], v[156:157], 0, s[6:7]
	global_load_dwordx4 v[96:99], v[84:85], off
	global_load_dwordx4 v[92:95], v[84:85], off offset:1024
	global_load_dwordx4 v[88:91], v[84:85], off offset:2048
	s_nop 0
	global_load_dwordx4 v[84:87], v[84:85], off offset:3072
	s_cmp_gt_i32 s18, s13
	s_cbranch_scc1 .Lidx_exit_prev1
	s_waitcnt vmcnt(15)
	v_mfma_f32_32x32x16_bf16 v[20:35], v[44:47], v[112:115], 0
	s_waitcnt vmcnt(14)
	v_mfma_f32_32x32x16_bf16 v[20:35], v[48:51], v[108:111], v[20:35]
	s_waitcnt vmcnt(13)
	v_mfma_f32_32x32x16_bf16 v[20:35], v[52:55], v[104:107], v[20:35]
	s_waitcnt vmcnt(12)
	v_mfma_f32_32x32x16_bf16 v[20:35], v[56:59], v[100:103], v[20:35]
	v_max_i32_e32 v177, 0, v4
	v_max_i32_e32 v176, 0, v12
	v_max_i32_e32 v179, 0, v5
	v_pk_fma_f32 v[176:177], v[134:135], v[176:177], 0 op_sel_hi:[1,1,0]
	v_max_i32_e32 v178, 0, v13
	v_max_i32_e32 v181, 0, v6
	v_max_i32_e32 v180, 0, v14
	v_pk_fma_f32 v[176:177], v[36:37], v[178:179], v[176:177]
	v_lshl_or_b32 v188, s14, 5, v164
	v_pk_fma_f32 v[176:177], v[136:137], v[180:181], v[176:177]
	v_max_i32_e32 v179, 0, v7
	v_max_i32_e32 v178, 0, v15
	v_pk_fma_f32 v[176:177], v[38:39], v[178:179], v[176:177]
	v_max_i32_e32 v179, 0, v8
	v_max_i32_e32 v178, 0, v16
	v_pk_fma_f32 v[176:177], v[138:139], v[178:179], v[176:177]
	v_max_i32_e32 v179, 0, v9
	v_max_i32_e32 v178, 0, v17
	v_pk_fma_f32 v[176:177], v[40:41], v[178:179], v[176:177]
	v_max_i32_e32 v179, 0, v10
	v_max_i32_e32 v178, 0, v18
	v_pk_fma_f32 v[176:177], v[140:141], v[178:179], v[176:177]
	v_max_i32_e32 v179, 0, v11
	v_max_i32_e32 v178, 0, v19
	v_pk_fma_f32 v[176:177], v[42:43], v[178:179], v[176:177]
	s_nop 0
	v_and_b32_e32 v183, 0x7fffffff, v177
	v_and_b32_e32 v182, 0x7fffffff, v176
	v_xor_b32_e32 v185, -1, v177
	v_pk_add_f32 v[182:183], v[182:183], 0 neg_lo:[1,1] neg_hi:[1,1]
	v_cmp_gt_i32_e32 vcc, 0, v177
	v_xor_b32_e32 v184, -1, v176
	s_nop 0
	v_cndmask_b32_e32 v186, v183, v185, vcc
	v_cmp_gt_i32_e32 vcc, 0, v176
	s_nop 1
	v_cndmask_b32_e32 v187, v182, v184, vcc
	v_cmp_le_i32_e32 vcc, v188, v132
	s_nop 1
	v_cndmask_b32_e32 v187, 0, v187, vcc
	v_cmp_le_i32_e32 vcc, v188, v1
	v_lshl_add_u32 v189, s14, 7, v175
	s_nop 0
	v_cndmask_b32_e32 v186, 0, v186, vcc
	ds_write2st64_b32 v189, v186, v187 offset1:128
	v_lshrrev_b32_e32 v190, 20, v186
	v_cmp_eq_u32_e32 vcc, 0, v186
	v_lshrrev_b32_e32 v191, 17, v186
	v_and_b32_e32 v190, 0xffc, v190
	v_and_b32_e32 v191, 16, v191
	v_add_u32_e32 v190, v165, v190
	v_lshlrev_b32_e64 v191, v191, 1
	v_cndmask_b32_e32 v190, v190, v166, vcc
	v_cndmask_b32_e64 v191, v191, 0, vcc
	ds_add_u32 v190, v191
	v_lshrrev_b32_e32 v190, 20, v187
	v_cmp_eq_u32_e32 vcc, 0, v187
	v_lshrrev_b32_e32 v191, 17, v187
	v_and_b32_e32 v190, 0xffc, v190
	v_and_b32_e32 v191, 16, v191
	v_add3_u32 v190, v165, v190, s73
	v_lshlrev_b32_e64 v191, v191, 1
	v_cndmask_b32_e32 v190, v190, v166, vcc
	v_cndmask_b32_e64 v191, v191, 0, vcc
	ds_add_u32 v190, v191
	s_waitcnt lgkmcnt(3)
	v_readfirstlane_b32 s15, v171
	s_mov_b32 s14, s18
	s_mov_b32 s18, s15
	s_mov_b64 exec, 1
	ds_add_rtn_u32 v171, v172, v149
	s_mov_b64 exec, -1
	s_min_i32 s6, s18, s13
	s_ashr_i32 s7, s6, 31
	s_lshl_b64 s[6:7], s[6:7], 12
	s_waitcnt vmcnt(12)
	v_lshl_add_u64 v[100:101], v[156:157], 0, s[6:7]
	global_load_dwordx4 v[112:115], v[100:101], off
	global_load_dwordx4 v[108:111], v[100:101], off offset:1024
	global_load_dwordx4 v[104:107], v[100:101], off offset:2048
	s_nop 0
	global_load_dwordx4 v[100:103], v[100:101], off offset:3072
	s_cmp_gt_i32 s19, s13
	s_cbranch_scc1 .Lidx_exit_prev0
	s_waitcnt vmcnt(15)
	v_mfma_f32_32x32x16_bf16 v[4:19], v[44:47], v[128:131], 0
	s_waitcnt vmcnt(14)
	v_mfma_f32_32x32x16_bf16 v[4:19], v[48:51], v[124:127], v[4:19]
	s_waitcnt vmcnt(13)
	v_mfma_f32_32x32x16_bf16 v[4:19], v[52:55], v[120:123], v[4:19]
	s_waitcnt vmcnt(12)
	v_mfma_f32_32x32x16_bf16 v[4:19], v[56:59], v[116:119], v[4:19]
	v_max_i32_e32 v177, 0, v20
	v_max_i32_e32 v176, 0, v28
	v_max_i32_e32 v179, 0, v21
	v_pk_fma_f32 v[176:177], v[134:135], v[176:177], 0 op_sel_hi:[1,1,0]
	v_max_i32_e32 v178, 0, v29
	v_max_i32_e32 v181, 0, v22
	v_max_i32_e32 v180, 0, v30
	v_pk_fma_f32 v[176:177], v[36:37], v[178:179], v[176:177]
	v_lshl_or_b32 v188, s14, 5, v164
	v_pk_fma_f32 v[176:177], v[136:137], v[180:181], v[176:177]
	v_max_i32_e32 v179, 0, v23
	v_max_i32_e32 v178, 0, v31
	v_pk_fma_f32 v[176:177], v[38:39], v[178:179], v[176:177]
	v_max_i32_e32 v179, 0, v24
	v_max_i32_e32 v178, 0, v32
	v_pk_fma_f32 v[176:177], v[138:139], v[178:179], v[176:177]
	v_max_i32_e32 v179, 0, v25
	v_max_i32_e32 v178, 0, v33
	v_pk_fma_f32 v[176:177], v[40:41], v[178:179], v[176:177]
	v_max_i32_e32 v179, 0, v26
	v_max_i32_e32 v178, 0, v34
	v_pk_fma_f32 v[176:177], v[140:141], v[178:179], v[176:177]
	v_max_i32_e32 v179, 0, v27
	v_max_i32_e32 v178, 0, v35
	v_pk_fma_f32 v[176:177], v[42:43], v[178:179], v[176:177]
	s_nop 0
	v_and_b32_e32 v183, 0x7fffffff, v177
	v_and_b32_e32 v182, 0x7fffffff, v176
	v_xor_b32_e32 v185, -1, v177
	v_pk_add_f32 v[182:183], v[182:183], 0 neg_lo:[1,1] neg_hi:[1,1]
	v_cmp_gt_i32_e32 vcc, 0, v177
	v_xor_b32_e32 v184, -1, v176
	s_nop 0
	v_cndmask_b32_e32 v186, v183, v185, vcc
	v_cmp_gt_i32_e32 vcc, 0, v176
	s_nop 1
	v_cndmask_b32_e32 v187, v182, v184, vcc
	v_cmp_le_i32_e32 vcc, v188, v132
	s_nop 1
	v_cndmask_b32_e32 v187, 0, v187, vcc
	v_cmp_le_i32_e32 vcc, v188, v1
	v_lshl_add_u32 v189, s14, 7, v175
	s_nop 0
	v_cndmask_b32_e32 v186, 0, v186, vcc
	ds_write2st64_b32 v189, v186, v187 offset1:128
	v_lshrrev_b32_e32 v190, 20, v186
	v_cmp_eq_u32_e32 vcc, 0, v186
	v_lshrrev_b32_e32 v191, 17, v186
	v_and_b32_e32 v190, 0xffc, v190
	v_and_b32_e32 v191, 16, v191
	v_add_u32_e32 v190, v165, v190
	v_lshlrev_b32_e64 v191, v191, 1
	v_cndmask_b32_e32 v190, v190, v166, vcc
	v_cndmask_b32_e64 v191, v191, 0, vcc
	ds_add_u32 v190, v191
	v_lshrrev_b32_e32 v190, 20, v187
	v_cmp_eq_u32_e32 vcc, 0, v187
	v_lshrrev_b32_e32 v191, 17, v187
	v_and_b32_e32 v190, 0xffc, v190
	v_and_b32_e32 v191, 16, v191
	v_add3_u32 v190, v165, v190, s73
	v_lshlrev_b32_e64 v191, v191, 1
	v_cndmask_b32_e32 v190, v190, v166, vcc
	v_cndmask_b32_e64 v191, v191, 0, vcc
	ds_add_u32 v190, v191
	s_waitcnt lgkmcnt(3)
	v_readfirstlane_b32 s15, v171
	s_add_i32 s10, s10, 1
	s_cmpk_lt_i32 s10, 0x400
	s_cbranch_scc1 .Lidx_loop
	s_branch .Lidx_done
.Lidx_exit_prev1:
	s_cmp_lt_i32 s14, 0
	s_cbranch_scc1 .Lidx_done
	v_max_i32_e32 v177, 0, v4
	v_max_i32_e32 v176, 0, v12
	v_max_i32_e32 v179, 0, v5
	v_pk_fma_f32 v[176:177], v[134:135], v[176:177], 0 op_sel_hi:[1,1,0]
	v_max_i32_e32 v178, 0, v13
	v_max_i32_e32 v181, 0, v6
	v_max_i32_e32 v180, 0, v14
	v_pk_fma_f32 v[176:177], v[36:37], v[178:179], v[176:177]
	v_lshl_or_b32 v188, s14, 5, v164
	v_pk_fma_f32 v[176:177], v[136:137], v[180:181], v[176:177]
	v_max_i32_e32 v179, 0, v7
	v_max_i32_e32 v178, 0, v15
	v_pk_fma_f32 v[176:177], v[38:39], v[178:179], v[176:177]
	v_max_i32_e32 v179, 0, v8
	v_max_i32_e32 v178, 0, v16
	v_pk_fma_f32 v[176:177], v[138:139], v[178:179], v[176:177]
	v_max_i32_e32 v179, 0, v9
	v_max_i32_e32 v178, 0, v17
	v_pk_fma_f32 v[176:177], v[40:41], v[178:179], v[176:177]
	v_max_i32_e32 v179, 0, v10
	v_max_i32_e32 v178, 0, v18
	v_pk_fma_f32 v[176:177], v[140:141], v[178:179], v[176:177]
	v_max_i32_e32 v179, 0, v11
	v_max_i32_e32 v178, 0, v19
	v_pk_fma_f32 v[176:177], v[42:43], v[178:179], v[176:177]
	s_nop 0
	v_and_b32_e32 v183, 0x7fffffff, v177
	v_and_b32_e32 v182, 0x7fffffff, v176
	v_xor_b32_e32 v185, -1, v177
	v_pk_add_f32 v[182:183], v[182:183], 0 neg_lo:[1,1] neg_hi:[1,1]
	v_cmp_gt_i32_e32 vcc, 0, v177
	v_xor_b32_e32 v184, -1, v176
	s_nop 0
	v_cndmask_b32_e32 v186, v183, v185, vcc
	v_cmp_gt_i32_e32 vcc, 0, v176
	s_nop 1
	v_cndmask_b32_e32 v187, v182, v184, vcc
	v_cmp_le_i32_e32 vcc, v188, v132
	s_nop 1
	v_cndmask_b32_e32 v187, 0, v187, vcc
	v_cmp_le_i32_e32 vcc, v188, v1
	v_lshl_add_u32 v189, s14, 7, v175
	s_nop 0
	v_cndmask_b32_e32 v186, 0, v186, vcc
	ds_write2st64_b32 v189, v186, v187 offset1:128
	v_lshrrev_b32_e32 v190, 20, v186
	v_cmp_eq_u32_e32 vcc, 0, v186
	v_lshrrev_b32_e32 v191, 17, v186
	v_and_b32_e32 v190, 0xffc, v190
	v_and_b32_e32 v191, 16, v191
	v_add_u32_e32 v190, v165, v190
	v_lshlrev_b32_e64 v191, v191, 1
	v_cndmask_b32_e32 v190, v190, v166, vcc
	v_cndmask_b32_e64 v191, v191, 0, vcc
	ds_add_u32 v190, v191
	v_lshrrev_b32_e32 v190, 20, v187
	v_cmp_eq_u32_e32 vcc, 0, v187
	v_lshrrev_b32_e32 v191, 17, v187
	v_and_b32_e32 v190, 0xffc, v190
	v_and_b32_e32 v191, 16, v191
	v_add3_u32 v190, v165, v190, s73
	v_lshlrev_b32_e64 v191, v191, 1
	v_cndmask_b32_e32 v190, v190, v166, vcc
	v_cndmask_b32_e64 v191, v191, 0, vcc
	ds_add_u32 v190, v191
	s_branch .Lidx_done
.Lidx_exit_prev0:
	v_max_i32_e32 v177, 0, v20
	v_max_i32_e32 v176, 0, v28
	v_max_i32_e32 v179, 0, v21
	v_pk_fma_f32 v[176:177], v[134:135], v[176:177], 0 op_sel_hi:[1,1,0]
	v_max_i32_e32 v178, 0, v29
	v_max_i32_e32 v181, 0, v22
	v_max_i32_e32 v180, 0, v30
	v_pk_fma_f32 v[176:177], v[36:37], v[178:179], v[176:177]
	v_lshl_or_b32 v188, s14, 5, v164
	v_pk_fma_f32 v[176:177], v[136:137], v[180:181], v[176:177]
	v_max_i32_e32 v179, 0, v23
	v_max_i32_e32 v178, 0, v31
	v_pk_fma_f32 v[176:177], v[38:39], v[178:179], v[176:177]
	v_max_i32_e32 v179, 0, v24
	v_max_i32_e32 v178, 0, v32
	v_pk_fma_f32 v[176:177], v[138:139], v[178:179], v[176:177]
	v_max_i32_e32 v179, 0, v25
	v_max_i32_e32 v178, 0, v33
	v_pk_fma_f32 v[176:177], v[40:41], v[178:179], v[176:177]
	v_max_i32_e32 v179, 0, v26
	v_max_i32_e32 v178, 0, v34
	v_pk_fma_f32 v[176:177], v[140:141], v[178:179], v[176:177]
	v_max_i32_e32 v179, 0, v27
	v_max_i32_e32 v178, 0, v35
	v_pk_fma_f32 v[176:177], v[42:43], v[178:179], v[176:177]
	s_nop 0
	v_and_b32_e32 v183, 0x7fffffff, v177
	v_and_b32_e32 v182, 0x7fffffff, v176
	v_xor_b32_e32 v185, -1, v177
	v_pk_add_f32 v[182:183], v[182:183], 0 neg_lo:[1,1] neg_hi:[1,1]
	v_cmp_gt_i32_e32 vcc, 0, v177
	v_xor_b32_e32 v184, -1, v176
	s_nop 0
	v_cndmask_b32_e32 v186, v183, v185, vcc
	v_cmp_gt_i32_e32 vcc, 0, v176
	s_nop 1
	v_cndmask_b32_e32 v187, v182, v184, vcc
	v_cmp_le_i32_e32 vcc, v188, v132
	s_nop 1
	v_cndmask_b32_e32 v187, 0, v187, vcc
	v_cmp_le_i32_e32 vcc, v188, v1
	v_lshl_add_u32 v189, s14, 7, v175
	s_nop 0
	v_cndmask_b32_e32 v186, 0, v186, vcc
	ds_write2st64_b32 v189, v186, v187 offset1:128
	v_lshrrev_b32_e32 v190, 20, v186
	v_cmp_eq_u32_e32 vcc, 0, v186
	v_lshrrev_b32_e32 v191, 17, v186
	v_and_b32_e32 v190, 0xffc, v190
	v_and_b32_e32 v191, 16, v191
	v_add_u32_e32 v190, v165, v190
	v_lshlrev_b32_e64 v191, v191, 1
	v_cndmask_b32_e32 v190, v190, v166, vcc
	v_cndmask_b32_e64 v191, v191, 0, vcc
	ds_add_u32 v190, v191
	v_lshrrev_b32_e32 v190, 20, v187
	v_cmp_eq_u32_e32 vcc, 0, v187
	v_lshrrev_b32_e32 v191, 17, v187
	v_and_b32_e32 v190, 0xffc, v190
	v_and_b32_e32 v191, 16, v191
	v_add3_u32 v190, v165, v190, s73
	v_lshlrev_b32_e64 v191, v191, 1
	v_cndmask_b32_e32 v190, v190, v166, vcc
	v_cndmask_b32_e64 v191, v191, 0, vcc
	ds_add_u32 v190, v191
.Lidx_done:
.LBB0_719:
	s_add_i32 s87, s12, 1
	s_bitcmp0_b32 s12, 0
	s_mov_b64 s[10:11], -1
	s_cselect_b64 s[6:7], -1, 0
	s_and_b64 vcc, exec, s[48:49]
	s_cbranch_vccnz .LBB0_799
	s_andn2_b64 vcc, exec, s[10:11]
	s_cbranch_vccz .LBB0_800

.LBB0_722:
	s_ashr_i32 s57, s56, 31
	s_lshl_b64 s[6:7], s[56:57], 13
	s_ashr_i32 s10, s88, 31
	v_lshrrev_b32_e32 v3, 1, v144
	s_add_u32 s11, s6, s88
	v_and_b32_e32 v1, 3, v144
	v_and_b32_e32 v4, 2, v3
	v_lshrrev_b32_e32 v5, 4, v164
	s_addc_u32 s10, s7, s10
	v_and_or_b32 v1, v3, 4, v1
	v_or3_b32 v3, v4, v5, s11
	v_mov_b64_e32 v[4:5], s[38:39]
	v_mad_u64_u32 v[8:9], s[6:7], v3, s74, v[4:5]
	v_or_b32_e32 v4, s11, v163
	v_mov_b32_e32 v5, s10
	v_lshlrev_b64 v[4:5], 5, v[4:5]
	v_lshl_add_u64 v[6:7], s[42:43], 0, v[4:5]
	v_or_b32_e32 v4, 32, v4
	v_lshl_add_u64 v[10:11], s[42:43], 0, v[4:5]
	global_load_dwordx4 v[36:39], v[6:7], off
	global_load_dwordx4 v[40:43], v[6:7], off offset:16
	v_mad_i32_i24 v9, s10, v151, v9
	global_load_dwordx4 v[134:137], v[10:11], off
	v_lshlrev_b32_e32 v132, 7, v1
	v_lshl_add_u64 v[8:9], v[8:9], 0, v[132:133]
	v_lshlrev_b32_e32 v132, 4, v162
	v_lshl_add_u64 v[12:13], v[8:9], 0, v[132:133]
	global_load_dwordx4 v[138:141], v[10:11], off offset:16
	s_nop 0
	global_load_dwordx4 v[44:47], v[12:13], off offset:3072
	global_load_dwordx4 v[48:51], v[12:13], off offset:3104
	global_load_dwordx4 v[52:55], v[12:13], off offset:3136
	global_load_dwordx4 v[56:59], v[12:13], off offset:3168
